# v15 plus attention selection-mask apply rewritten from v_and/v_cmp/s_nop/v_cndmask VCC chain to v_bfe_i32+v_bfi_b32 (symbolically verified equivalent), MFMA-to-VALU distance re-padded
# speedup vs baseline: 1.0080x; 1.0080x over previous
; #define LAS __attribute__((address_space(3)))
; __device__ __forceinline__ void partialSM(f32x16& p0, f32x16& p1, float& m_reg, float& mn, float& alpha) {
;   constexpr float C = SCALE * 1.4426950408889634f;
;   float pmax = p0[0];
; #pragma unroll
;   for (int r = 1; r < 16; ++r) pmax = fmaxf(pmax, p0[r]);
; #pragma unroll
;   for (int r = 0; r < 16; ++r) pmax = fmaxf(pmax, p1[r]);
;   { auto rr = __builtin_amdgcn_permlane32_swap(__float_as_uint(pmax), __float_as_uint(pmax), false, false);
;     pmax = fmaxf(__uint_as_float(rr[0]), __uint_as_float(rr[1])); }
;   if (__builtin_expect(__all(pmax - m_reg <= THR / SCALE), 1)) { mn = m_reg; alpha = 1.f; }
;   else { mn = fmaxf(m_reg, pmax); alpha = __builtin_amdgcn_exp2f((m_reg - mn) * C); m_reg = mn; }
; __device__ __forceinline__ void qkt(f32x16& p0, f32x16& p1, const LAS unsigned char* Ks, const bf16x8* qr, int r32, int hi, unsigned long long mw) {
; #pragma unroll
;   for (int r = 0; r < 16; ++r) { p0[r] = 0.f; p1[r] = 0.f; }
; #pragma unroll
;   for (int d0 = 0; d0 < 8; ++d0) { int cb = (d0 * 16 + hi * 8) * 2;
;     bf16x8 b0 = *reinterpret_cast<const LAS bf16x8*>(Ks + KSWZ(r32, cb));
;     bf16x8 b1 = *reinterpret_cast<const LAS bf16x8*>(Ks + KSWZ(32 + r32, cb));
;     p0 = __builtin_amdgcn_mfma_f32_32x32x16_bf16(b0, qr[d0], p0, 0, 0, 0);
;     p1 = __builtin_amdgcn_mfma_f32_32x32x16_bf16(b1, qr[d0], p1, 0, 0, 0); }
;   const unsigned lo = (unsigned)mw >> (4 * hi), hw = (unsigned)(mw >> 32) >> (4 * hi);
;   const float ninf = -__builtin_inff();
; #pragma unroll
;   for (int r = 0; r < 16; ++r) { const int bit = (r & 3) + 8 * (r >> 2); p0[r] = ((lo >> bit) & 1u) ? p0[r] : ninf; p1[r] = ((hw >> bit) & 1u) ? p1[r] : ninf; }
.LBB0_962:
	v_cndmask_b32_e64 v2, 0, 1, s[58:59]
	v_cmp_ne_u32_e64 s[6:7], 1, v2
	s_andn2_b64 vcc, exec, s[58:59]
	s_cbranch_vccnz .LBB0_968
	v_add_u32_e32 v2, v202, v203
	ds_read_b128 v[68:71], v2 offset:32768
	ds_read_b128 v[84:87], v2 offset:40960
	v_add_u32_e32 v2, v202, v204
	ds_read_b128 v[220:223], v2 offset:32768
	ds_read_b128 v[240:243], v2 offset:40960
	v_add_u32_e32 v2, v202, v205
	s_waitcnt lgkmcnt(3)
	v_mfma_f32_32x32x16_bf16 v[68:83], v[68:71], v[100:103], 0
	v_add_u32_e32 v187, -8, v185
	s_waitcnt lgkmcnt(2)
	v_mfma_f32_32x32x16_bf16 v[84:99], v[84:87], v[100:103], 0
	s_waitcnt lgkmcnt(1)
	v_mfma_f32_32x32x16_bf16 v[68:83], v[220:223], v[104:107], v[68:83]
	s_waitcnt lgkmcnt(0)
	v_mfma_f32_32x32x16_bf16 v[84:99], v[240:243], v[104:107], v[84:99]
	ds_read_b128 v[220:223], v2 offset:32768
	ds_read_b128 v[240:243], v2 offset:40960
	v_add_u32_e32 v2, v202, v206
	s_waitcnt lgkmcnt(1)
	v_mfma_f32_32x32x16_bf16 v[68:83], v[220:223], v[108:111], v[68:83]
	s_waitcnt lgkmcnt(0)
	v_mfma_f32_32x32x16_bf16 v[84:99], v[240:243], v[108:111], v[84:99]
	ds_read_b128 v[220:223], v2 offset:32768
	ds_read_b128 v[240:243], v2 offset:40960
	v_add_u32_e32 v2, v202, v207
	s_waitcnt lgkmcnt(1)
	v_mfma_f32_32x32x16_bf16 v[68:83], v[220:223], v[112:115], v[68:83]
	s_waitcnt lgkmcnt(0)
	v_mfma_f32_32x32x16_bf16 v[84:99], v[240:243], v[112:115], v[84:99]
	ds_read_b128 v[220:223], v2 offset:32768
	ds_read_b128 v[240:243], v2 offset:40960
	v_add_u32_e32 v2, v202, v208
	s_waitcnt lgkmcnt(1)
	v_mfma_f32_32x32x16_bf16 v[68:83], v[220:223], v[116:119], v[68:83]
	s_waitcnt lgkmcnt(0)
	v_mfma_f32_32x32x16_bf16 v[84:99], v[240:243], v[116:119], v[84:99]
	ds_read_b128 v[220:223], v2 offset:32768
	ds_read_b128 v[240:243], v2 offset:40960
	v_add_u32_e32 v2, v202, v209
	s_waitcnt lgkmcnt(1)
	v_mfma_f32_32x32x16_bf16 v[68:83], v[220:223], v[120:123], v[68:83]
	s_waitcnt lgkmcnt(0)
	v_mfma_f32_32x32x16_bf16 v[84:99], v[240:243], v[120:123], v[84:99]
	ds_read_b128 v[220:223], v2 offset:32768
	ds_read_b128 v[240:243], v2 offset:40960
	v_add_u32_e32 v2, v202, v210
	s_waitcnt lgkmcnt(1)
	v_mfma_f32_32x32x16_bf16 v[68:83], v[220:223], v[124:127], v[68:83]
	ds_read_b128 v[220:223], v2 offset:32768
	s_waitcnt lgkmcnt(1)
	v_mfma_f32_32x32x16_bf16 v[84:99], v[240:243], v[124:127], v[84:99]
	ds_read_b128 v[240:243], v2 offset:40960
	s_waitcnt lgkmcnt(1)
	v_mfma_f32_32x32x16_bf16 v[68:83], v[220:223], v[128:131], v[68:83]
	ds_read_b64 v[220:221], v187
	s_waitcnt lgkmcnt(0)
	v_lshrrev_b32_e32 v194, v211, v220
	v_lshrrev_b32_e32 v220, v211, v221
	v_mfma_f32_32x32x16_bf16 v[84:99], v[240:243], v[128:131], v[84:99]
	v_bfe_i32 v187, v194, 0, 1
	s_nop 5
	v_bfi_b32 v187, v187, v68, v229
	v_bfe_i32 v2, v220, 0, 1
	s_nop 2
	v_bfi_b32 v2, v2, v84, v229
	v_bfe_i32 v84, v194, 1, 1
	v_bfi_b32 v84, v84, v69, v229
	v_bfe_i32 v68, v220, 1, 1
	v_bfi_b32 v68, v68, v85, v229
	v_bfe_i32 v85, v194, 2, 1
	v_bfi_b32 v85, v85, v70, v229
	v_bfe_i32 v69, v220, 2, 1
	v_bfi_b32 v69, v69, v86, v229
	v_bfe_i32 v86, v194, 3, 1
	v_bfi_b32 v86, v86, v71, v229
	v_bfe_i32 v70, v220, 3, 1
	v_bfi_b32 v70, v70, v87, v229
	v_bfe_i32 v87, v194, 8, 1
	v_bfi_b32 v87, v87, v72, v229
	v_bfe_i32 v71, v220, 8, 1
	v_bfi_b32 v71, v71, v88, v229
	v_bfe_i32 v88, v194, 9, 1
	v_bfi_b32 v88, v88, v73, v229
	v_bfe_i32 v72, v220, 9, 1
	v_bfi_b32 v72, v72, v89, v229
	v_bfe_i32 v89, v194, 10, 1
	v_bfi_b32 v89, v89, v74, v229
	v_bfe_i32 v73, v220, 10, 1
	v_bfi_b32 v73, v73, v90, v229
	v_bfe_i32 v90, v194, 11, 1
	v_bfi_b32 v90, v90, v75, v229
	v_bfe_i32 v74, v220, 11, 1
	v_bfi_b32 v74, v74, v91, v229
	v_bfe_i32 v91, v194, 16, 1
	v_bfi_b32 v91, v91, v76, v229
	v_bfe_i32 v75, v220, 16, 1
	v_bfi_b32 v75, v75, v92, v229
	v_bfe_i32 v92, v194, 17, 1
	v_bfi_b32 v92, v92, v77, v229
	v_bfe_i32 v77, v220, 17, 1
	v_bfi_b32 v77, v77, v93, v229
	v_bfe_i32 v93, v194, 18, 1
	v_bfi_b32 v93, v93, v78, v229
	v_bfe_i32 v78, v220, 18, 1
	v_bfi_b32 v78, v78, v94, v229
	v_bfe_i32 v94, v194, 19, 1
	v_bfi_b32 v94, v94, v79, v229
	v_bfe_i32 v79, v220, 19, 1
	v_bfi_b32 v79, v79, v95, v229
	v_bfe_i32 v95, v194, 24, 1
	v_bfi_b32 v95, v95, v80, v229
	v_bfe_i32 v80, v220, 24, 1
	v_bfi_b32 v80, v80, v96, v229
	v_bfe_i32 v96, v194, 25, 1
	v_bfi_b32 v96, v96, v81, v229
	v_bfe_i32 v81, v220, 25, 1
	v_bfi_b32 v81, v81, v97, v229
	v_bfe_i32 v97, v194, 26, 1
	v_bfi_b32 v97, v97, v82, v229
	v_bfe_i32 v82, v220, 26, 1
	v_bfi_b32 v82, v82, v98, v229
	v_bfe_i32 v98, v194, 27, 1
	v_bfi_b32 v98, v98, v83, v229
	v_max_f32_e32 v76, v84, v84
	v_bfe_i32 v83, v220, 27, 1
	v_bfi_b32 v83, v83, v99, v229
	v_max_f32_e32 v99, v187, v187
	v_max_f32_e32 v76, v99, v76
	v_max3_f32 v76, v76, v85, v86
	v_max3_f32 v76, v76, v87, v88
	v_max3_f32 v76, v76, v89, v90
	v_max3_f32 v76, v76, v91, v92
	v_max3_f32 v76, v76, v93, v94
	v_max3_f32 v76, v76, v95, v96
	v_max3_f32 v76, v76, v97, v98
	v_max3_f32 v76, v76, v2, v68
	v_max3_f32 v76, v76, v69, v70
	v_max3_f32 v76, v76, v71, v72
	v_max3_f32 v76, v76, v73, v74
	v_max3_f32 v76, v76, v75, v77
	v_max3_f32 v76, v76, v78, v79
	v_max3_f32 v76, v76, v80, v81
	v_max3_f32 v76, v76, v82, v83
	v_mov_b32_e32 v99, v76
	s_nop 1
	v_permlane32_swap_b32_e32 v76, v99
	v_max_f32_e32 v99, v99, v99
	v_max_f32_e32 v76, v76, v76
	v_max_f32_e32 v76, v76, v99
	v_max_f32_e32 v99, v189, v189
	v_max_f32_e32 v99, v99, v76
	v_sub_f32_e32 v194, v76, v189
	v_sub_f32_e32 v76, v189, v99
	v_mul_f32_e32 v76, 0x3e0293ee, v76
	v_exp_f32_e32 v76, v76
	v_cmp_ge_f32_e32 vcc, s69, v194
	s_cmp_eq_u64 vcc, exec
	s_cselect_b64 s[8:9], -1, 0
	v_cndmask_b32_e64 v76, v76, 1.0, s[8:9]
	v_cmp_gt_f32_e32 vcc, 1.0, v76
	s_cbranch_vccz .LBB0_967
	s_and_saveexec_b64 s[34:35], s[4:5]
	ds_write_b32 v212, v76 offset:128
	s_or_b64 exec, exec, s[34:35]
	s_waitcnt lgkmcnt(0)
	ds_read_b128 v[220:223], v214 offset:224
	ds_read_b128 v[240:243], v214 offset:192
	ds_read_b128 v[244:247], v214 offset:160
	ds_read_b128 v[248:251], v214 offset:128
	s_waitcnt lgkmcnt(3)
	v_pk_mul_f32 v[66:67], v[66:67], v[222:223]
	s_waitcnt lgkmcnt(2)
	v_pk_mul_f32 v[62:63], v[62:63], v[242:243]
	s_waitcnt lgkmcnt(1)
	v_pk_mul_f32 v[58:59], v[58:59], v[246:247]
	s_waitcnt lgkmcnt(0)
	v_pk_mul_f32 v[54:55], v[54:55], v[250:251]
	v_pk_mul_f32 v[64:65], v[64:65], v[220:221]
	v_pk_mul_f32 v[60:61], v[60:61], v[240:241]
	v_pk_mul_f32 v[56:57], v[56:57], v[244:245]
	v_pk_mul_f32 v[52:53], v[52:53], v[248:249]
	v_pk_mul_f32 v[50:51], v[50:51], v[222:223]
	v_pk_mul_f32 v[46:47], v[46:47], v[242:243]
	v_pk_mul_f32 v[42:43], v[42:43], v[246:247]
	v_pk_mul_f32 v[38:39], v[38:39], v[250:251]
	v_pk_mul_f32 v[48:49], v[48:49], v[220:221]
	v_pk_mul_f32 v[44:45], v[44:45], v[240:241]
	v_pk_mul_f32 v[40:41], v[40:41], v[244:245]
	v_pk_mul_f32 v[36:37], v[36:37], v[248:249]
	v_pk_mul_f32 v[34:35], v[34:35], v[222:223]
	v_pk_mul_f32 v[30:31], v[30:31], v[242:243]
	v_pk_mul_f32 v[26:27], v[26:27], v[246:247]
	v_pk_mul_f32 v[22:23], v[22:23], v[250:251]
	v_pk_mul_f32 v[32:33], v[32:33], v[220:221]
	v_pk_mul_f32 v[28:29], v[28:29], v[240:241]
	v_pk_mul_f32 v[24:25], v[24:25], v[244:245]
	v_pk_mul_f32 v[20:21], v[20:21], v[248:249]
	v_pk_mul_f32 v[18:19], v[18:19], v[222:223]
	v_pk_mul_f32 v[14:15], v[14:15], v[242:243]
	v_pk_mul_f32 v[10:11], v[10:11], v[246:247]
	v_pk_mul_f32 v[6:7], v[6:7], v[250:251]
	v_pk_mul_f32 v[16:17], v[16:17], v[220:221]
	v_pk_mul_f32 v[12:13], v[12:13], v[240:241]
	v_pk_mul_f32 v[8:9], v[8:9], v[244:245]
	v_pk_mul_f32 v[4:5], v[4:5], v[248:249]

; #define LAS __attribute__((address_space(3)))
; __device__ __forceinline__ void partialSM(f32x16& p0, f32x16& p1, float& m_reg, float& mn, float& alpha) {
;   constexpr float C = SCALE * 1.4426950408889634f;
;   float pmax = p0[0];
; #pragma unroll
;   for (int r = 1; r < 16; ++r) pmax = fmaxf(pmax, p0[r]);
; #pragma unroll
;   for (int r = 0; r < 16; ++r) pmax = fmaxf(pmax, p1[r]);
;   { auto rr = __builtin_amdgcn_permlane32_swap(__float_as_uint(pmax), __float_as_uint(pmax), false, false);
;     pmax = fmaxf(__uint_as_float(rr[0]), __uint_as_float(rr[1])); }
;   if (__builtin_expect(__all(pmax - m_reg <= THR / SCALE), 1)) { mn = m_reg; alpha = 1.f; }
;   else { mn = fmaxf(m_reg, pmax); alpha = __builtin_amdgcn_exp2f((m_reg - mn) * C); m_reg = mn; }
; __device__ __forceinline__ void qkt(f32x16& p0, f32x16& p1, const LAS unsigned char* Ks, const bf16x8* qr, int r32, int hi, unsigned long long mw) {
; #pragma unroll
;   for (int r = 0; r < 16; ++r) { p0[r] = 0.f; p1[r] = 0.f; }
; #pragma unroll
;   for (int d0 = 0; d0 < 8; ++d0) { int cb = (d0 * 16 + hi * 8) * 2;
;     bf16x8 b0 = *reinterpret_cast<const LAS bf16x8*>(Ks + KSWZ(r32, cb));
;     bf16x8 b1 = *reinterpret_cast<const LAS bf16x8*>(Ks + KSWZ(32 + r32, cb));
;     p0 = __builtin_amdgcn_mfma_f32_32x32x16_bf16(b0, qr[d0], p0, 0, 0, 0);
;     p1 = __builtin_amdgcn_mfma_f32_32x32x16_bf16(b1, qr[d0], p1, 0, 0, 0); }
;   const unsigned lo = (unsigned)mw >> (4 * hi), hw = (unsigned)(mw >> 32) >> (4 * hi);
;   const float ninf = -__builtin_inff();
; #pragma unroll
;   for (int r = 0; r < 16; ++r) { const int bit = (r & 3) + 8 * (r >> 2); p0[r] = ((lo >> bit) & 1u) ? p0[r] : ninf; p1[r] = ((hw >> bit) & 1u) ? p1[r] : ninf; }
.LBB0_970:
	s_and_b64 vcc, exec, s[6:7]
	s_cbranch_vccnz .LBB0_959
	v_add_u32_e32 v2, v202, v203
	ds_read_b128 v[68:71], v2 offset:49152
	ds_read_b128 v[84:87], v2 offset:57344
	v_add_u32_e32 v2, v202, v204
	ds_read_b128 v[220:223], v2 offset:49152
	ds_read_b128 v[240:243], v2 offset:57344
	v_add_u32_e32 v2, v202, v205
	s_waitcnt lgkmcnt(3)
	v_mfma_f32_32x32x16_bf16 v[68:83], v[68:71], v[100:103], 0
	s_waitcnt lgkmcnt(2)
	v_mfma_f32_32x32x16_bf16 v[84:99], v[84:87], v[100:103], 0
	s_waitcnt lgkmcnt(1)
	v_mfma_f32_32x32x16_bf16 v[68:83], v[220:223], v[104:107], v[68:83]
	s_waitcnt lgkmcnt(0)
	v_mfma_f32_32x32x16_bf16 v[84:99], v[240:243], v[104:107], v[84:99]
	ds_read_b128 v[220:223], v2 offset:49152
	ds_read_b128 v[240:243], v2 offset:57344
	v_add_u32_e32 v2, v202, v206
	s_waitcnt lgkmcnt(1)
	v_mfma_f32_32x32x16_bf16 v[68:83], v[220:223], v[108:111], v[68:83]
	s_waitcnt lgkmcnt(0)
	v_mfma_f32_32x32x16_bf16 v[84:99], v[240:243], v[108:111], v[84:99]
	ds_read_b128 v[220:223], v2 offset:49152
	ds_read_b128 v[240:243], v2 offset:57344
	v_add_u32_e32 v2, v202, v207
	s_waitcnt lgkmcnt(1)
	v_mfma_f32_32x32x16_bf16 v[68:83], v[220:223], v[112:115], v[68:83]
	s_waitcnt lgkmcnt(0)
	v_mfma_f32_32x32x16_bf16 v[84:99], v[240:243], v[112:115], v[84:99]
	ds_read_b128 v[220:223], v2 offset:49152
	ds_read_b128 v[240:243], v2 offset:57344
	v_add_u32_e32 v2, v202, v208
	s_waitcnt lgkmcnt(1)
	v_mfma_f32_32x32x16_bf16 v[68:83], v[220:223], v[116:119], v[68:83]
	s_waitcnt lgkmcnt(0)
	v_mfma_f32_32x32x16_bf16 v[84:99], v[240:243], v[116:119], v[84:99]
	ds_read_b128 v[220:223], v2 offset:49152
	ds_read_b128 v[240:243], v2 offset:57344
	v_add_u32_e32 v2, v202, v209
	s_waitcnt lgkmcnt(1)
	v_mfma_f32_32x32x16_bf16 v[68:83], v[220:223], v[120:123], v[68:83]
	s_waitcnt lgkmcnt(0)
	v_mfma_f32_32x32x16_bf16 v[84:99], v[240:243], v[120:123], v[84:99]
	ds_read_b128 v[220:223], v2 offset:49152
	ds_read_b128 v[240:243], v2 offset:57344
	v_add_u32_e32 v2, v202, v210
	s_waitcnt lgkmcnt(1)
	v_mfma_f32_32x32x16_bf16 v[68:83], v[220:223], v[124:127], v[68:83]
	s_waitcnt lgkmcnt(0)
	v_mfma_f32_32x32x16_bf16 v[84:99], v[240:243], v[124:127], v[84:99]
	ds_read_b128 v[220:223], v2 offset:49152
	ds_read_b128 v[240:243], v2 offset:57344
	s_waitcnt lgkmcnt(1)
	v_mfma_f32_32x32x16_bf16 v[68:83], v[220:223], v[128:131], v[68:83]
	ds_read_b64 v[220:221], v185
	s_waitcnt lgkmcnt(0)
	v_lshrrev_b32_e32 v194, v211, v220
	v_lshrrev_b32_e32 v220, v211, v221
	v_mfma_f32_32x32x16_bf16 v[84:99], v[240:243], v[128:131], v[84:99]
	v_bfe_i32 v187, v194, 0, 1
	s_nop 5
	v_bfi_b32 v187, v187, v68, v229
	v_bfe_i32 v2, v220, 0, 1
	s_nop 2
	v_bfi_b32 v2, v2, v84, v229
	v_bfe_i32 v84, v194, 1, 1
	v_bfi_b32 v84, v84, v69, v229
	v_bfe_i32 v68, v220, 1, 1
	v_bfi_b32 v68, v68, v85, v229
	v_bfe_i32 v85, v194, 2, 1
	v_bfi_b32 v85, v85, v70, v229
	v_bfe_i32 v69, v220, 2, 1
	v_bfi_b32 v69, v69, v86, v229
	v_bfe_i32 v86, v194, 3, 1
	v_bfi_b32 v86, v86, v71, v229
	v_bfe_i32 v70, v220, 3, 1
	v_bfi_b32 v70, v70, v87, v229
	v_bfe_i32 v87, v194, 8, 1
	v_bfi_b32 v87, v87, v72, v229
	v_bfe_i32 v71, v220, 8, 1
	v_bfi_b32 v71, v71, v88, v229
	v_bfe_i32 v88, v194, 9, 1
	v_bfi_b32 v88, v88, v73, v229
	v_bfe_i32 v72, v220, 9, 1
	v_bfi_b32 v72, v72, v89, v229
	v_bfe_i32 v89, v194, 10, 1
	v_bfi_b32 v89, v89, v74, v229
	v_bfe_i32 v73, v220, 10, 1
	v_bfi_b32 v73, v73, v90, v229
	v_bfe_i32 v90, v194, 11, 1
	v_bfi_b32 v90, v90, v75, v229
	v_bfe_i32 v74, v220, 11, 1
	v_bfi_b32 v74, v74, v91, v229
	v_bfe_i32 v91, v194, 16, 1
	v_bfi_b32 v91, v91, v76, v229
	v_bfe_i32 v75, v220, 16, 1
	v_bfi_b32 v75, v75, v92, v229
	v_bfe_i32 v92, v194, 17, 1
	v_bfi_b32 v92, v92, v77, v229
	v_bfe_i32 v77, v220, 17, 1
	v_bfi_b32 v77, v77, v93, v229
	v_bfe_i32 v93, v194, 18, 1
	v_bfi_b32 v93, v93, v78, v229
	v_bfe_i32 v78, v220, 18, 1
	v_bfi_b32 v78, v78, v94, v229
	v_bfe_i32 v94, v194, 19, 1
	v_bfi_b32 v94, v94, v79, v229
	v_bfe_i32 v79, v220, 19, 1
	v_bfi_b32 v79, v79, v95, v229
	v_bfe_i32 v95, v194, 24, 1
	v_bfi_b32 v95, v95, v80, v229
	v_bfe_i32 v80, v220, 24, 1
	v_bfi_b32 v80, v80, v96, v229
	v_bfe_i32 v96, v194, 25, 1
	v_bfi_b32 v96, v96, v81, v229
	v_bfe_i32 v81, v220, 25, 1
	v_bfi_b32 v81, v81, v97, v229
	v_bfe_i32 v97, v194, 26, 1
	v_bfi_b32 v97, v97, v82, v229
	v_bfe_i32 v82, v220, 26, 1
	v_bfi_b32 v82, v82, v98, v229
	v_bfe_i32 v98, v194, 27, 1
	v_bfi_b32 v98, v98, v83, v229
	v_max_f32_e32 v76, v84, v84
	v_bfe_i32 v83, v220, 27, 1
	v_bfi_b32 v83, v83, v99, v229
	v_max_f32_e32 v99, v187, v187
	v_max_f32_e32 v76, v99, v76
	v_max3_f32 v76, v76, v85, v86
	v_max3_f32 v76, v76, v87, v88
	v_max3_f32 v76, v76, v89, v90
	v_max3_f32 v76, v76, v91, v92
	v_max3_f32 v76, v76, v93, v94
	v_max3_f32 v76, v76, v95, v96
	v_max3_f32 v76, v76, v97, v98
	v_max3_f32 v76, v76, v2, v68
	v_max3_f32 v76, v76, v69, v70
	v_max3_f32 v76, v76, v71, v72
	v_max3_f32 v76, v76, v73, v74
	v_max3_f32 v76, v76, v75, v77
	v_max3_f32 v76, v76, v78, v79
	v_max3_f32 v76, v76, v80, v81
	v_max3_f32 v76, v76, v82, v83
	v_mov_b32_e32 v99, v76
	s_nop 1
	v_permlane32_swap_b32_e32 v76, v99
	v_max_f32_e32 v99, v99, v99
	v_max_f32_e32 v76, v76, v76
	v_max_f32_e32 v76, v76, v99
	v_max_f32_e32 v99, v189, v189
	v_max_f32_e32 v99, v99, v76
	v_sub_f32_e32 v194, v76, v189
	v_sub_f32_e32 v76, v189, v99
	v_mul_f32_e32 v76, 0x3e0293ee, v76
	v_exp_f32_e32 v76, v76
	v_cmp_ge_f32_e32 vcc, s69, v194
	s_cmp_eq_u64 vcc, exec
	s_cselect_b64 s[6:7], -1, 0
	v_cndmask_b32_e64 v76, v76, 1.0, s[6:7]
	v_cmp_gt_f32_e32 vcc, 1.0, v76
	s_cbranch_vccz .LBB0_958
	s_and_saveexec_b64 s[8:9], s[4:5]
	s_cbranch_execz .LBB0_957
	ds_write_b32 v212, v76 offset:128
	s_branch .LBB0_957

; #define LAS __attribute__((address_space(3)))
; __device__ __forceinline__ void partialSM(f32x16& p0, f32x16& p1, float& m_reg, float& mn, float& alpha) {
;   constexpr float C = SCALE * 1.4426950408889634f;
;   float pmax = p0[0];
; #pragma unroll
;   for (int r = 1; r < 16; ++r) pmax = fmaxf(pmax, p0[r]);
; #pragma unroll
;   for (int r = 0; r < 16; ++r) pmax = fmaxf(pmax, p1[r]);
;   { auto rr = __builtin_amdgcn_permlane32_swap(__float_as_uint(pmax), __float_as_uint(pmax), false, false);
;     pmax = fmaxf(__uint_as_float(rr[0]), __uint_as_float(rr[1])); }
;   if (__builtin_expect(__all(pmax - m_reg <= THR / SCALE), 1)) { mn = m_reg; alpha = 1.f; }
;   else { mn = fmaxf(m_reg, pmax); alpha = __builtin_amdgcn_exp2f((m_reg - mn) * C); m_reg = mn; }
; __device__ __forceinline__ void qkt(f32x16& p0, f32x16& p1, const LAS unsigned char* Ks, const bf16x8* qr, int r32, int hi, unsigned long long mw) {
; #pragma unroll
;   for (int r = 0; r < 16; ++r) { p0[r] = 0.f; p1[r] = 0.f; }
; #pragma unroll
;   for (int d0 = 0; d0 < 8; ++d0) { int cb = (d0 * 16 + hi * 8) * 2;
;     bf16x8 b0 = *reinterpret_cast<const LAS bf16x8*>(Ks + KSWZ(r32, cb));
;     bf16x8 b1 = *reinterpret_cast<const LAS bf16x8*>(Ks + KSWZ(32 + r32, cb));
;     p0 = __builtin_amdgcn_mfma_f32_32x32x16_bf16(b0, qr[d0], p0, 0, 0, 0);
;     p1 = __builtin_amdgcn_mfma_f32_32x32x16_bf16(b1, qr[d0], p1, 0, 0, 0); }
;   const unsigned lo = (unsigned)mw >> (4 * hi), hw = (unsigned)(mw >> 32) >> (4 * hi);
;   const float ninf = -__builtin_inff();
; #pragma unroll
;   for (int r = 0; r < 16; ++r) { const int bit = (r & 3) + 8 * (r >> 2); p0[r] = ((lo >> bit) & 1u) ? p0[r] : ninf; p1[r] = ((hw >> bit) & 1u) ? p1[r] : ninf; }
.LBB0_988:
	v_add_u32_e32 v2, s8, v201
	v_add_u32_e32 v72, v2, v203
	ds_read_b128 v[68:71], v72 offset:32768
	ds_read_b128 v[84:87], v72 offset:40960
	v_add_u32_e32 v194, v2, v204
	ds_read_b128 v[240:243], v194 offset:32768
	ds_read_b128 v[244:247], v194 offset:40960
	v_add_u32_e32 v194, v2, v205
	s_waitcnt lgkmcnt(3)
	v_mfma_f32_32x32x16_bf16 v[68:83], v[68:71], v[128:131], 0
	s_waitcnt lgkmcnt(2)
	v_mfma_f32_32x32x16_bf16 v[84:99], v[84:87], v[128:131], 0
	s_waitcnt lgkmcnt(1)
	v_mfma_f32_32x32x16_bf16 v[68:83], v[240:243], v[124:127], v[68:83]
	s_waitcnt lgkmcnt(0)
	v_mfma_f32_32x32x16_bf16 v[84:99], v[244:247], v[124:127], v[84:99]
	ds_read_b128 v[240:243], v194 offset:32768
	ds_read_b128 v[244:247], v194 offset:40960
	v_add_u32_e32 v194, v2, v206
	s_waitcnt lgkmcnt(1)
	v_mfma_f32_32x32x16_bf16 v[68:83], v[240:243], v[120:123], v[68:83]
	s_waitcnt lgkmcnt(0)
	v_mfma_f32_32x32x16_bf16 v[84:99], v[244:247], v[120:123], v[84:99]
	ds_read_b128 v[240:243], v194 offset:32768
	ds_read_b128 v[244:247], v194 offset:40960
	v_add_u32_e32 v194, v2, v207
	s_waitcnt lgkmcnt(1)
	v_mfma_f32_32x32x16_bf16 v[68:83], v[240:243], v[116:119], v[68:83]
	s_waitcnt lgkmcnt(0)
	v_mfma_f32_32x32x16_bf16 v[84:99], v[244:247], v[116:119], v[84:99]
	ds_read_b128 v[240:243], v194 offset:32768
	ds_read_b128 v[244:247], v194 offset:40960
	v_add_u32_e32 v194, v2, v208
	s_waitcnt lgkmcnt(1)
	v_mfma_f32_32x32x16_bf16 v[68:83], v[240:243], v[112:115], v[68:83]
	s_waitcnt lgkmcnt(0)
	v_mfma_f32_32x32x16_bf16 v[84:99], v[244:247], v[112:115], v[84:99]
	ds_read_b128 v[240:243], v194 offset:32768
	ds_read_b128 v[244:247], v194 offset:40960
	v_add_u32_e32 v194, v2, v209
	v_add_u32_e32 v2, v2, v210
	s_waitcnt lgkmcnt(1)
	v_mfma_f32_32x32x16_bf16 v[68:83], v[240:243], v[108:111], v[68:83]
	s_waitcnt lgkmcnt(0)
	v_mfma_f32_32x32x16_bf16 v[84:99], v[244:247], v[108:111], v[84:99]
	ds_read_b128 v[240:243], v194 offset:32768
	ds_read_b128 v[244:247], v194 offset:40960
	s_waitcnt lgkmcnt(1)
	v_mfma_f32_32x32x16_bf16 v[68:83], v[240:243], v[104:107], v[68:83]
	s_waitcnt lgkmcnt(0)
	v_mfma_f32_32x32x16_bf16 v[84:99], v[244:247], v[104:107], v[84:99]
	ds_read_b128 v[240:243], v2 offset:32768
	ds_read_b128 v[244:247], v2 offset:40960
	ds_read_b64 v[220:221], v233
	s_waitcnt lgkmcnt(0)
	v_lshrrev_b32_e32 v194, v211, v220
	v_mfma_f32_32x32x16_bf16 v[68:83], v[240:243], v[100:103], v[68:83]
	v_lshrrev_b32_e32 v220, v211, v221
	v_mfma_f32_32x32x16_bf16 v[84:99], v[244:247], v[100:103], v[84:99]
	v_bfe_i32 v239, v194, 0, 1
	s_nop 8
	v_bfi_b32 v239, v239, v68, v229
	v_bfe_i32 v2, v220, 0, 1
	v_bfi_b32 v2, v2, v84, v229
	v_bfe_i32 v84, v194, 1, 1
	v_bfi_b32 v84, v84, v69, v229
	v_bfe_i32 v68, v220, 1, 1
	v_bfi_b32 v68, v68, v85, v229
	v_bfe_i32 v85, v194, 2, 1
	v_bfi_b32 v85, v85, v70, v229
	v_bfe_i32 v69, v220, 2, 1
	v_bfi_b32 v69, v69, v86, v229
	v_bfe_i32 v86, v194, 3, 1
	v_bfi_b32 v86, v86, v71, v229
	v_bfe_i32 v70, v220, 3, 1
	v_bfi_b32 v70, v70, v87, v229
	v_bfe_i32 v87, v194, 8, 1
	v_bfi_b32 v87, v87, v72, v229
	v_bfe_i32 v71, v220, 8, 1
	v_bfi_b32 v71, v71, v88, v229
	v_bfe_i32 v88, v194, 9, 1
	v_bfi_b32 v88, v88, v73, v229
	v_bfe_i32 v72, v220, 9, 1
	v_bfi_b32 v72, v72, v89, v229
	v_bfe_i32 v89, v194, 10, 1
	v_bfi_b32 v89, v89, v74, v229
	v_bfe_i32 v73, v220, 10, 1
	v_bfi_b32 v73, v73, v90, v229
	v_bfe_i32 v90, v194, 11, 1
	v_bfi_b32 v90, v90, v75, v229
	v_bfe_i32 v74, v220, 11, 1
	v_bfi_b32 v74, v74, v91, v229
	v_bfe_i32 v91, v194, 16, 1
	v_bfi_b32 v91, v91, v76, v229
	v_bfe_i32 v75, v220, 16, 1
	v_bfi_b32 v75, v75, v92, v229
	v_bfe_i32 v92, v194, 17, 1
	v_bfi_b32 v92, v92, v77, v229
	v_bfe_i32 v77, v220, 17, 1
	v_bfi_b32 v77, v77, v93, v229
	v_bfe_i32 v93, v194, 18, 1
	v_bfi_b32 v93, v93, v78, v229
	v_bfe_i32 v78, v220, 18, 1
	v_bfi_b32 v78, v78, v94, v229
	v_bfe_i32 v94, v194, 19, 1
	v_bfi_b32 v94, v94, v79, v229
	v_bfe_i32 v79, v220, 19, 1
	v_bfi_b32 v79, v79, v95, v229
	v_bfe_i32 v95, v194, 24, 1
	v_bfi_b32 v95, v95, v80, v229
	v_bfe_i32 v80, v220, 24, 1
	v_bfi_b32 v80, v80, v96, v229
	v_bfe_i32 v96, v194, 25, 1
	v_bfi_b32 v96, v96, v81, v229
	v_bfe_i32 v81, v220, 25, 1
	v_bfi_b32 v81, v81, v97, v229
	v_bfe_i32 v97, v194, 26, 1
	v_bfi_b32 v97, v97, v82, v229
	v_bfe_i32 v82, v220, 26, 1
	v_bfi_b32 v82, v82, v98, v229
	v_bfe_i32 v98, v194, 27, 1
	v_bfi_b32 v98, v98, v83, v229
	v_max_f32_e32 v76, v84, v84
	v_bfe_i32 v83, v220, 27, 1
	v_bfi_b32 v83, v83, v99, v229
	v_max_f32_e32 v99, v239, v239
	v_max_f32_e32 v76, v99, v76
	v_max3_f32 v76, v76, v85, v86
	v_max3_f32 v76, v76, v87, v88
	v_max3_f32 v76, v76, v89, v90
	v_max3_f32 v76, v76, v91, v92
	v_max3_f32 v76, v76, v93, v94
	v_max3_f32 v76, v76, v95, v96
	v_max3_f32 v76, v76, v97, v98
	v_max3_f32 v76, v76, v2, v68
	v_max3_f32 v76, v76, v69, v70
	v_max3_f32 v76, v76, v71, v72
	v_max3_f32 v76, v76, v73, v74
	v_max3_f32 v76, v76, v75, v77
	v_max3_f32 v76, v76, v78, v79
	v_max3_f32 v76, v76, v80, v81
	v_max3_f32 v76, v76, v82, v83
	v_mov_b32_e32 v99, v76
	s_nop 1
	v_permlane32_swap_b32_e32 v76, v99
	v_max_f32_e32 v99, v99, v99
	v_max_f32_e32 v76, v76, v76
	v_max_f32_e32 v76, v76, v99
	v_max_f32_e32 v99, v232, v232
	v_max_f32_e32 v99, v99, v76
	v_sub_f32_e32 v194, v76, v232
	v_sub_f32_e32 v76, v232, v99
	v_mul_f32_e32 v76, 0x3e0293ee, v76
	v_exp_f32_e32 v76, v76
	v_cmp_ge_f32_e32 vcc, s69, v194
	s_cmp_eq_u64 vcc, exec
	s_cselect_b64 s[8:9], -1, 0
	v_cndmask_b32_e64 v76, v76, 1.0, s[8:9]
	v_cmp_gt_f32_e32 vcc, 1.0, v76
	s_cbranch_vccz .LBB0_981
	s_and_saveexec_b64 s[34:35], s[4:5]
	s_cbranch_execz .LBB0_980
	ds_write_b32 v212, v76 offset:128
	s_branch .LBB0_980
; #define LAS __attribute__((address_space(3)))
; __device__ __forceinline__ void qkt(f32x16& p0, f32x16& p1, const LAS unsigned char* Ks, const bf16x8* qr, int r32, int hi, unsigned long long mw) {
; #pragma unroll
;   for (int r = 0; r < 16; ++r) { p0[r] = 0.f; p1[r] = 0.f; }
; #pragma unroll
;   for (int d0 = 0; d0 < 8; ++d0) { int cb = (d0 * 16 + hi * 8) * 2;
;     bf16x8 b0 = *reinterpret_cast<const LAS bf16x8*>(Ks + KSWZ(r32, cb));
;     bf16x8 b1 = *reinterpret_cast<const LAS bf16x8*>(Ks + KSWZ(32 + r32, cb));
;     p0 = __builtin_amdgcn_mfma_f32_32x32x16_bf16(b0, qr[d0], p0, 0, 0, 0);
;     p1 = __builtin_amdgcn_mfma_f32_32x32x16_bf16(b1, qr[d0], p1, 0, 0, 0); }
;   const unsigned lo = (unsigned)mw >> (4 * hi), hw = (unsigned)(mw >> 32) >> (4 * hi);
;   const float ninf = -__builtin_inff();
; #pragma unroll
;   for (int r = 0; r < 16; ++r) { const int bit = (r & 3) + 8 * (r >> 2); p0[r] = ((lo >> bit) & 1u) ? p0[r] : ninf; p1[r] = ((hw >> bit) & 1u) ? p1[r] : ninf; }
.LBB0_991:
	s_waitcnt vmcnt(7)
	v_cvt_pk_bf16_f32 v68, v156, v157
	v_cvt_pk_bf16_f32 v69, v158, v159
	s_waitcnt vmcnt(6)
	v_cvt_pk_bf16_f32 v70, v148, v149
	v_cvt_pk_bf16_f32 v71, v150, v151
	ds_write_b128 v252, v[68:71] offset:16384
	s_waitcnt vmcnt(5)
	v_cvt_pk_bf16_f32 v68, v160, v161
	v_cvt_pk_bf16_f32 v69, v162, v163
	s_waitcnt vmcnt(4)
	v_cvt_pk_bf16_f32 v70, v152, v153
	v_cvt_pk_bf16_f32 v71, v154, v155
	ds_write_b128 v253, v[68:71] offset:16384
	s_waitcnt vmcnt(3)
	v_cvt_pk_bf16_f32 v68, v140, v141
	v_cvt_pk_bf16_f32 v69, v142, v143
	s_waitcnt vmcnt(2)
	v_cvt_pk_bf16_f32 v70, v132, v133
	v_cvt_pk_bf16_f32 v71, v134, v135
	ds_write_b128 v254, v[68:71] offset:49152
	s_waitcnt vmcnt(1)
	v_cvt_pk_bf16_f32 v68, v144, v145
	s_and_b64 vcc, exec, s[6:7]
	v_cvt_pk_bf16_f32 v69, v146, v147
	s_waitcnt vmcnt(0)
	v_cvt_pk_bf16_f32 v70, v136, v137
	v_cvt_pk_bf16_f32 v71, v138, v139
	ds_write_b128 v195, v[68:71] offset:49152
	s_waitcnt lgkmcnt(0)
	s_barrier
	s_cbranch_vccnz .LBB0_999
	v_add_u32_e32 v2, v202, v203
	ds_read_b128 v[68:71], v2 offset:49152
	ds_read_b128 v[84:87], v2 offset:57344
	v_mul_lo_u32 v72, v230, s39
	v_add_u32_e32 v72, s66, v72
	v_add_u32_e32 v2, v202, v204
	ds_read_b64 v[136:137], v72 offset:264
	ds_read_b128 v[132:135], v2 offset:49152
	s_waitcnt lgkmcnt(3)
	v_mfma_f32_32x32x16_bf16 v[68:83], v[68:71], v[128:131], 0
	s_waitcnt lgkmcnt(2)
	v_mfma_f32_32x32x16_bf16 v[84:99], v[84:87], v[128:131], 0
	ds_read_b128 v[128:131], v2 offset:57344
	v_add_u32_e32 v2, v202, v205
	s_waitcnt lgkmcnt(1)
	v_mfma_f32_32x32x16_bf16 v[68:83], v[132:135], v[124:127], v[68:83]
	ds_read_b128 v[132:135], v2 offset:49152
	s_waitcnt lgkmcnt(1)
	v_mfma_f32_32x32x16_bf16 v[84:99], v[128:131], v[124:127], v[84:99]
	ds_read_b128 v[124:127], v2 offset:57344
	v_add_u32_e32 v2, v202, v206
	ds_read_b128 v[128:131], v2 offset:49152
	s_waitcnt lgkmcnt(2)
	v_mfma_f32_32x32x16_bf16 v[68:83], v[132:135], v[120:123], v[68:83]
	s_waitcnt lgkmcnt(1)
	v_mfma_f32_32x32x16_bf16 v[84:99], v[124:127], v[120:123], v[84:99]
	ds_read_b128 v[120:123], v2 offset:57344
	v_add_u32_e32 v2, v202, v207
	ds_read_b128 v[124:127], v2 offset:49152
	s_waitcnt lgkmcnt(2)
	v_mfma_f32_32x32x16_bf16 v[68:83], v[128:131], v[116:119], v[68:83]
	s_waitcnt lgkmcnt(1)
	v_mfma_f32_32x32x16_bf16 v[84:99], v[120:123], v[116:119], v[84:99]
	ds_read_b128 v[116:119], v2 offset:57344
	v_add_u32_e32 v2, v202, v208
	ds_read_b128 v[120:123], v2 offset:49152
	s_waitcnt lgkmcnt(2)
	v_mfma_f32_32x32x16_bf16 v[68:83], v[124:127], v[112:115], v[68:83]
	s_waitcnt lgkmcnt(1)
	v_mfma_f32_32x32x16_bf16 v[84:99], v[116:119], v[112:115], v[84:99]
	ds_read_b128 v[112:115], v2 offset:57344
	v_add_u32_e32 v2, v202, v209
	ds_read_b128 v[116:119], v2 offset:49152
	s_waitcnt lgkmcnt(2)
	v_mfma_f32_32x32x16_bf16 v[68:83], v[120:123], v[108:111], v[68:83]
	s_waitcnt lgkmcnt(1)
	v_mfma_f32_32x32x16_bf16 v[84:99], v[112:115], v[108:111], v[84:99]
	ds_read_b128 v[108:111], v2 offset:57344
	v_add_u32_e32 v2, v202, v210
	ds_read_b128 v[112:115], v2 offset:49152
	s_waitcnt lgkmcnt(2)
	v_mfma_f32_32x32x16_bf16 v[68:83], v[116:119], v[104:107], v[68:83]
	s_waitcnt lgkmcnt(1)
	v_mfma_f32_32x32x16_bf16 v[84:99], v[108:111], v[104:107], v[84:99]
	ds_read_b128 v[106:109], v2 offset:57344
	v_lshrrev_b32_e32 v2, v211, v136
	v_lshrrev_b32_e32 v105, v211, v137
	s_waitcnt lgkmcnt(1)
	v_mfma_f32_32x32x16_bf16 v[68:83], v[112:115], v[100:103], v[68:83]
	s_waitcnt lgkmcnt(0)
	v_mfma_f32_32x32x16_bf16 v[84:99], v[106:109], v[100:103], v[84:99]
	v_bfe_i32 v104, v2, 0, 1
	s_nop 8
	v_bfi_b32 v104, v104, v68, v229
	v_bfe_i32 v68, v105, 0, 1
	v_bfi_b32 v68, v68, v84, v229
	v_bfe_i32 v84, v2, 1, 1
	v_bfi_b32 v84, v84, v69, v229
	v_bfe_i32 v69, v105, 1, 1
	v_bfi_b32 v69, v69, v85, v229
	v_bfe_i32 v85, v2, 2, 1
	v_bfi_b32 v85, v85, v70, v229
	v_bfe_i32 v70, v105, 2, 1
	v_bfi_b32 v70, v70, v86, v229
	v_bfe_i32 v86, v2, 3, 1
	v_bfi_b32 v86, v86, v71, v229
	v_bfe_i32 v71, v105, 3, 1
	v_bfi_b32 v71, v71, v87, v229
	v_bfe_i32 v87, v2, 8, 1
	v_bfi_b32 v87, v87, v72, v229
	v_bfe_i32 v72, v105, 8, 1
	v_bfi_b32 v72, v72, v88, v229
	v_bfe_i32 v88, v2, 9, 1
	v_bfi_b32 v88, v88, v73, v229
	v_bfe_i32 v73, v105, 9, 1
	v_bfi_b32 v73, v73, v89, v229
	v_bfe_i32 v89, v2, 10, 1
	v_bfi_b32 v89, v89, v74, v229
	v_bfe_i32 v74, v105, 10, 1
	v_bfi_b32 v74, v74, v90, v229
	v_bfe_i32 v90, v2, 11, 1
	v_bfi_b32 v90, v90, v75, v229
	v_bfe_i32 v75, v105, 11, 1
	v_bfi_b32 v75, v75, v91, v229
	v_bfe_i32 v91, v2, 16, 1
	v_bfi_b32 v91, v91, v76, v229
	v_bfe_i32 v76, v105, 16, 1
	v_bfi_b32 v76, v76, v92, v229
	v_bfe_i32 v92, v2, 17, 1
	v_bfi_b32 v92, v92, v77, v229
	v_bfe_i32 v77, v105, 17, 1
	v_bfi_b32 v77, v77, v93, v229
	v_bfe_i32 v93, v2, 18, 1
	v_bfi_b32 v93, v93, v78, v229
	v_bfe_i32 v78, v105, 18, 1
	v_bfi_b32 v78, v78, v94, v229
	v_bfe_i32 v94, v2, 19, 1
	v_bfi_b32 v94, v94, v79, v229
	v_bfe_i32 v79, v105, 19, 1
	v_bfi_b32 v79, v79, v95, v229
	v_bfe_i32 v95, v2, 24, 1
	v_bfi_b32 v95, v95, v80, v229
	v_bfe_i32 v80, v105, 24, 1
	v_bfi_b32 v80, v80, v96, v229
	v_bfe_i32 v96, v2, 25, 1
	v_bfi_b32 v96, v96, v81, v229
	v_bfe_i32 v81, v105, 25, 1
	v_bfi_b32 v81, v81, v97, v229
	v_bfe_i32 v97, v2, 26, 1
	v_bfi_b32 v97, v97, v82, v229
	v_bfe_i32 v82, v105, 26, 1
	v_bfi_b32 v82, v82, v98, v229
	v_bfe_i32 v98, v2, 27, 1
	v_bfi_b32 v98, v98, v83, v229
	v_max_f32_e32 v2, v84, v84
	v_bfe_i32 v83, v105, 27, 1
	v_bfi_b32 v83, v83, v99, v229
	v_max_f32_e32 v99, v104, v104
	v_max_f32_e32 v2, v99, v2
	v_max3_f32 v2, v2, v85, v86
	v_max3_f32 v2, v2, v87, v88
	v_max3_f32 v2, v2, v89, v90
	v_max3_f32 v2, v2, v91, v92
	v_max3_f32 v2, v2, v93, v94
	v_max3_f32 v2, v2, v95, v96
	v_max3_f32 v2, v2, v97, v98
	v_max3_f32 v2, v2, v68, v69
	v_max3_f32 v2, v2, v70, v71
	v_max3_f32 v2, v2, v72, v73
	v_max3_f32 v2, v2, v74, v75
	v_max3_f32 v2, v2, v76, v77
	v_max3_f32 v2, v2, v78, v79
	v_max3_f32 v2, v2, v80, v81
	v_max3_f32 v2, v2, v82, v83
	v_mov_b32_e32 v99, v2
	s_nop 1
	v_permlane32_swap_b32_e32 v2, v99
	v_max_f32_e32 v99, v99, v99
	v_max_f32_e32 v2, v2, v2
	v_max_f32_e32 v2, v2, v99
	v_max_f32_e32 v99, v232, v232
	v_max_f32_e32 v99, v99, v2
	v_sub_f32_e32 v100, v2, v232
	v_sub_f32_e32 v2, v232, v99
	v_mul_f32_e32 v2, 0x3e0293ee, v2
	v_exp_f32_e32 v2, v2
	v_cmp_ge_f32_e32 vcc, s69, v100
	s_cmp_eq_u64 vcc, exec
	s_cselect_b64 s[6:7], -1, 0
	v_cndmask_b32_e64 v2, v2, 1.0, s[6:7]
	v_cmp_gt_f32_e32 vcc, 1.0, v2
	s_cbranch_vccz .LBB0_996
	s_and_saveexec_b64 s[8:9], s[4:5]
	ds_write_b32 v212, v2 offset:128
	s_or_b64 exec, exec, s[8:9]
	s_waitcnt lgkmcnt(0)
	ds_read_b128 v[100:103], v214 offset:224
	ds_read_b128 v[106:109], v214 offset:192
	ds_read_b128 v[110:113], v214 offset:160
	ds_read_b128 v[114:117], v214 offset:128
	s_waitcnt lgkmcnt(3)
	v_pk_mul_f32 v[66:67], v[66:67], v[102:103]
	s_waitcnt lgkmcnt(2)
	v_pk_mul_f32 v[62:63], v[62:63], v[108:109]
	s_waitcnt lgkmcnt(1)
	v_pk_mul_f32 v[58:59], v[58:59], v[112:113]
	s_waitcnt lgkmcnt(0)
	v_pk_mul_f32 v[54:55], v[54:55], v[116:117]
	v_pk_mul_f32 v[64:65], v[64:65], v[100:101]
	v_pk_mul_f32 v[60:61], v[60:61], v[106:107]
	v_pk_mul_f32 v[56:57], v[56:57], v[110:111]
	v_pk_mul_f32 v[52:53], v[52:53], v[114:115]
	v_pk_mul_f32 v[50:51], v[50:51], v[102:103]
	v_pk_mul_f32 v[46:47], v[46:47], v[108:109]
	v_pk_mul_f32 v[42:43], v[42:43], v[112:113]
	v_pk_mul_f32 v[38:39], v[38:39], v[116:117]
	v_pk_mul_f32 v[48:49], v[48:49], v[100:101]
	v_pk_mul_f32 v[44:45], v[44:45], v[106:107]
	v_pk_mul_f32 v[40:41], v[40:41], v[110:111]
	v_pk_mul_f32 v[36:37], v[36:37], v[114:115]
	v_pk_mul_f32 v[34:35], v[34:35], v[102:103]
	v_pk_mul_f32 v[30:31], v[30:31], v[108:109]
	v_pk_mul_f32 v[26:27], v[26:27], v[112:113]
	v_pk_mul_f32 v[22:23], v[22:23], v[116:117]
	v_pk_mul_f32 v[32:33], v[32:33], v[100:101]
	v_pk_mul_f32 v[28:29], v[28:29], v[106:107]
	v_pk_mul_f32 v[24:25], v[24:25], v[110:111]
	v_pk_mul_f32 v[20:21], v[20:21], v[114:115]
	v_pk_mul_f32 v[18:19], v[18:19], v[102:103]
	v_pk_mul_f32 v[14:15], v[14:15], v[108:109]
	v_pk_mul_f32 v[10:11], v[10:11], v[112:113]
	v_pk_mul_f32 v[6:7], v[6:7], v[116:117]
	v_pk_mul_f32 v[16:17], v[16:17], v[100:101]
	v_pk_mul_f32 v[12:13], v[12:13], v[106:107]
	v_pk_mul_f32 v[8:9], v[8:9], v[110:111]
	v_pk_mul_f32 v[4:5], v[4:5], v[114:115]
